# one static s_setprio 1 for the younger wave half (waves 4-7) during the G1 and G3/C1 phases
# baseline (speedup 1.0000x reference)
; #define SEAM(k) do { if (IN(k) && IN((k) + 1)) { if (a.ph_hi > 4096) cg::this_grid().sync(); else xcd_barrier(xbar); } } while (0)
; __global__ void __launch_bounds__(512, 2) fwd_kernel(Args a) {
;     ...
;     if (IN(7)) { g1_phase(a, lds, G); } SEAM(7);
.LBB0_1470:
	v_readfirstlane_b32 s98, v1
	s_nop 3
	s_lshr_b32 s98, s98, 8
	s_cmp_eq_u32 s98, 1
	s_cbranch_scc0 .Lprio_skip_p7
	s_setprio 1

; __device__ __forceinline__ void xcd_barrier(const XcdBarrier& b) {
;     asm volatile("s_waitcnt vmcnt(0)" ::: "memory");
;     __syncthreads();
;     if (threadIdx.x == 0) {
;         unsigned* bar = b.bar;
;         __builtin_amdgcn_s_waitcnt(0);
;         unsigned nloc = b.st[0], nx = b.st[1];
;         if (nloc == 0u) { xcd_barrier_complete(bar, b.x, nloc, nx); b.st[0] = nloc; b.st[1] = nx; }
.LBB0_1549:
	s_setprio 0
	s_cmp_gt_i32 s91, 8
	s_cselect_b64 s[0:1], -1, 0
	s_and_b64 s[4:5], s[64:65], s[0:1]
	s_andn2_b64 vcc, exec, s[4:5]
	s_cbranch_vccnz .LBB0_1613
	s_cmpk_lt_u32 s91, 0x1001
	s_mov_b64 s[4:5], -1
	s_cbranch_scc0 .LBB0_1600
	s_waitcnt vmcnt(0)
	s_waitcnt vmcnt(0) lgkmcnt(0)
	s_barrier
	s_mov_b64 s[4:5], exec
	v_readlane_b32 s6, v242, 3
	v_readlane_b32 s7, v242, 4
	s_and_b64 s[6:7], s[4:5], s[6:7]
	s_mov_b64 exec, s[6:7]
	s_cbranch_execz .LBB0_1599
	s_add_i32 s3, 0, 0x23fc0
	v_mov_b32_e32 v2, s3
	s_waitcnt vmcnt(0) expcnt(0) lgkmcnt(0)
	ds_read_b32 v4, v2
	s_add_i32 s3, 0, 0x23fc4
	v_mov_b32_e32 v2, s3
	ds_read_b32 v2, v2
	s_waitcnt lgkmcnt(1)
	v_cmp_ne_u32_e32 vcc, 0, v4
	s_cbranch_vccnz .LBB0_1567
	v_readlane_b32 s6, v242, 0
	v_readlane_b32 s7, v242, 1
	s_load_dwordx2 s[10:11], s[6:7], 0x4
	s_add_u32 s6, s88, 0x1000
	s_addc_u32 s7, s89, 0
	s_add_u32 s8, s88, 0x1100
	s_addc_u32 s9, s89, 0
	s_waitcnt lgkmcnt(0)
	s_mul_i32 s3, s10, s50
	s_add_u32 s10, s88, 0x1200
	s_mul_i32 s3, s3, s11
	s_addc_u32 s11, s89, 0
	s_add_u32 s12, s88, 0x1300
	s_addc_u32 s13, s89, 0
	s_mov_b32 s20, 1
	v_mov_b32_e32 v18, 0
	s_branch .LBB0_1555

; __device__ __forceinline__ void xcd_barrier(const XcdBarrier& b) {
;     asm volatile("s_waitcnt vmcnt(0)" ::: "memory");
;     __syncthreads();
;     if (threadIdx.x == 0) {
;         unsigned* bar = b.bar;
;         __builtin_amdgcn_s_waitcnt(0);
;         unsigned nloc = b.st[0], nx = b.st[1];
;         if (nloc == 0u) { xcd_barrier_complete(bar, b.x, nloc, nx); b.st[0] = nloc; b.st[1] = nx; }
.LBB0_1712:
	s_setprio 0
	s_cmp_gt_i32 s91, 10
	s_cselect_b64 s[0:1], -1, 0
	s_and_b64 s[4:5], s[4:5], s[0:1]
	s_andn2_b64 vcc, exec, s[4:5]
	s_cbranch_vccnz .LBB0_1776
	s_cmpk_lt_u32 s91, 0x1001
	s_mov_b64 s[4:5], -1
	s_cbranch_scc0 .LBB0_1763
	s_waitcnt vmcnt(0)
	s_waitcnt vmcnt(0) lgkmcnt(0)
	s_barrier
	s_mov_b64 s[4:5], exec
	v_readlane_b32 s6, v242, 3
	v_readlane_b32 s7, v242, 4
	s_and_b64 s[6:7], s[4:5], s[6:7]
	s_mov_b64 exec, s[6:7]
	s_cbranch_execz .LBB0_1762
	s_add_i32 s3, 0, 0x23fc0
	v_mov_b32_e32 v2, s3
	s_waitcnt vmcnt(0) expcnt(0) lgkmcnt(0)
	ds_read_b32 v4, v2
	s_add_i32 s3, 0, 0x23fc4
	v_mov_b32_e32 v2, s3
	ds_read_b32 v2, v2
	s_waitcnt lgkmcnt(1)
	v_cmp_ne_u32_e32 vcc, 0, v4
	s_cbranch_vccnz .LBB0_1730
	v_readlane_b32 s6, v242, 0
	v_readlane_b32 s7, v242, 1
	s_load_dwordx2 s[10:11], s[6:7], 0x4
	s_add_u32 s6, s88, 0x1000
	s_addc_u32 s7, s89, 0
	s_add_u32 s8, s88, 0x1100
	s_addc_u32 s9, s89, 0
	s_waitcnt lgkmcnt(0)
	s_mul_i32 s3, s10, s50
	s_add_u32 s10, s88, 0x1200
	s_mul_i32 s3, s3, s11
	s_addc_u32 s11, s89, 0
	s_add_u32 s12, s88, 0x1300
	s_addc_u32 s13, s89, 0
	s_mov_b32 s20, 1
	v_mov_b32_e32 v18, 0
	s_branch .LBB0_1718
